# mqk bulk pull also covers the three causal-conv halo rows of the previous tile
# speedup vs baseline: 1.0093x; 1.0093x over previous
; #define MQ_LOAD(dst, mm) do { const int tk_ = row0 + 16 * (mm) + (lane & 15), s_ = tk_ & (SEQL - 1); \
;                 _Pragma("unroll") for (int j = 0; j < 4; ++j) dst[j] = (s_ - 3 + j >= 0) ? *(const u32x4*)(XM + (size_t)(tk_ - 3 + j) * 2048 + c0) : (u32x4){0u, 0u, 0u, 0u}; } while (0)
; __device__ void mqk_phase(const Params& p, unsigned char* smem) {
;     ...
;     for (int tile = blockIdx.x; tile < 256; tile += gridDim.x) {
;         const int row0 = tile * 64;
;         f32x4 acc[4];
; #pragma unroll
;         for (int m = 0; m < 4; ++m) acc[m] = (f32x4){0.f, 0.f, 0.f, 0.f};
;         for (int ks = 0; ks < 8; ++ks) {
;             const int c0 = 256 * wave + 32 * ks + 8 * (lane >> 4);
;             float cw[4][8], cbv[8];
; #pragma unroll
;             for (int j = 0; j < 4; ++j) { const f32x4 a = *(const f32x4*)(p.in[10] + j * 2048 + c0), b = *(const f32x4*)(p.in[10] + j * 2048 + c0 + 4);
; #pragma unroll
;                 for (int i = 0; i < 4; ++i) { cw[j][i] = a[i]; cw[j][4 + i] = b[i]; } }
;             { const f32x4 a = *(const f32x4*)(p.in[11] + c0), b = *(const f32x4*)(p.in[11] + c0 + 4);
; #pragma unroll
;               for (int i = 0; i < 4; ++i) { cbv[i] = a[i]; cbv[4 + i] = b[i]; } }
;             const bf16x8 bq = *(const bf16x8*)(WG + (size_t)(lane & 15) * 6144 + c0), bk = *(const bf16x8*)(WG + (size_t)(lane & 15) * 6144 + 2048 + c0), bv = *(const bf16x8*)(WG + (size_t)(lane & 15) * 6144 + 4096 + c0);
;             const float* wqp = p.in[12] + (size_t)(c0 >> 2) * 16; const float* wkp = p.in[13] + (size_t)(c0 >> 2) * 16; const float* wvp = p.in[14] + (size_t)(c0 >> 2) * 16;
;             u32x4 xraw[4];
;     ...
;             MQ_LOAD(xraw, 0);
.LBB0_299:
	s_lshl_b32 s2, s50, 18
	s_sub_i32 s2, s2, 0x3000
	s_max_i32 s2, s2, 0
	v_and_b32_e32 v130, 0x3ff, v0
	v_lshlrev_b32_e32 v130, 4, v130
	v_add_u32_e32 v130, s2, v130
	global_load_dwordx4 v[2:5], v130, s[0:1]
	v_add_u32_e32 v130, 0x2000, v130
	global_load_dwordx4 v[2:5], v130, s[0:1]
	v_add_u32_e32 v130, 0x2000, v130
	global_load_dwordx4 v[2:5], v130, s[0:1]
	v_add_u32_e32 v130, 0x2000, v130
	global_load_dwordx4 v[2:5], v130, s[0:1]
	v_add_u32_e32 v130, 0x2000, v130
	global_load_dwordx4 v[2:5], v130, s[0:1]
	v_add_u32_e32 v130, 0x2000, v130
	global_load_dwordx4 v[2:5], v130, s[0:1]
	v_add_u32_e32 v130, 0x2000, v130
	global_load_dwordx4 v[2:5], v130, s[0:1]
	v_add_u32_e32 v130, 0x2000, v130
	global_load_dwordx4 v[2:5], v130, s[0:1]
	v_add_u32_e32 v130, 0x2000, v130
	global_load_dwordx4 v[2:5], v130, s[0:1]
	v_add_u32_e32 v130, 0x2000, v130
	global_load_dwordx4 v[2:5], v130, s[0:1]
	v_add_u32_e32 v130, 0x2000, v130
	global_load_dwordx4 v[2:5], v130, s[0:1]
	v_add_u32_e32 v130, 0x2000, v130
	global_load_dwordx4 v[2:5], v130, s[0:1]
	v_add_u32_e32 v130, 0x2000, v130
	global_load_dwordx4 v[2:5], v130, s[0:1]
	v_add_u32_e32 v130, 0x2000, v130
	global_load_dwordx4 v[2:5], v130, s[0:1]
	v_add_u32_e32 v130, 0x2000, v130
	global_load_dwordx4 v[2:5], v130, s[0:1]
	v_add_u32_e32 v130, 0x2000, v130
	global_load_dwordx4 v[2:5], v130, s[0:1]
	v_add_u32_e32 v130, 0x2000, v130
	global_load_dwordx4 v[2:5], v130, s[0:1]
	v_add_u32_e32 v130, 0x2000, v130
	global_load_dwordx4 v[2:5], v130, s[0:1]
	v_add_u32_e32 v130, 0x2000, v130
	global_load_dwordx4 v[2:5], v130, s[0:1]
	v_add_u32_e32 v130, 0x2000, v130
	global_load_dwordx4 v[2:5], v130, s[0:1]
	v_add_u32_e32 v130, 0x2000, v130
	global_load_dwordx4 v[2:5], v130, s[0:1]
	v_add_u32_e32 v130, 0x2000, v130
	global_load_dwordx4 v[2:5], v130, s[0:1]
	v_add_u32_e32 v130, 0x2000, v130
	global_load_dwordx4 v[2:5], v130, s[0:1]
	v_add_u32_e32 v130, 0x2000, v130
	global_load_dwordx4 v[2:5], v130, s[0:1]
	v_add_u32_e32 v130, 0x2000, v130
	global_load_dwordx4 v[2:5], v130, s[0:1]
	v_add_u32_e32 v130, 0x2000, v130
	global_load_dwordx4 v[2:5], v130, s[0:1]
	v_add_u32_e32 v130, 0x2000, v130
	global_load_dwordx4 v[2:5], v130, s[0:1]
	v_add_u32_e32 v130, 0x2000, v130
	global_load_dwordx4 v[2:5], v130, s[0:1]
	v_add_u32_e32 v130, 0x2000, v130
	global_load_dwordx4 v[2:5], v130, s[0:1]
	v_add_u32_e32 v130, 0x2000, v130
	global_load_dwordx4 v[2:5], v130, s[0:1]
	v_add_u32_e32 v130, 0x2000, v130
	global_load_dwordx4 v[2:5], v130, s[0:1]
	v_add_u32_e32 v130, 0x2000, v130
	global_load_dwordx4 v[2:5], v130, s[0:1]
	v_add_u32_e32 v130, 0x2000, v130
	global_load_dwordx4 v[2:5], v130, s[0:1]
	v_add_u32_e32 v130, 0x2000, v130
	global_load_dwordx4 v[2:5], v130, s[0:1]
	v_add_u32_e32 v130, 0x2000, v130
	v_and_b32_e32 v118, 0x3ff, v0
	v_lshlrev_b32_e32 v118, 4, v118
	v_add_u32_e32 v119, 0x2000, v118
	v_add_u32_e32 v120, 0x4000, v118
	v_add_u32_e32 v121, 0x6000, v118
	global_load_dwordx4 v[70:73], v118, s[80:81]
	global_load_dwordx4 v[74:77], v119, s[80:81]
	global_load_dwordx4 v[78:81], v120, s[80:81]
	global_load_dwordx4 v[82:85], v121, s[80:81]
	global_load_dwordx4 v[86:89], v118, s[76:77]
	global_load_dwordx4 v[90:93], v119, s[76:77]
	global_load_dwordx4 v[94:97], v120, s[76:77]
	global_load_dwordx4 v[98:101], v121, s[76:77]
	global_load_dwordx4 v[102:105], v118, s[78:79]
	global_load_dwordx4 v[106:109], v119, s[78:79]
	global_load_dwordx4 v[110:113], v120, s[78:79]
	global_load_dwordx4 v[114:117], v121, s[78:79]
	s_waitcnt vmcnt(0)
	ds_write_b128 v118, v[70:73] offset:32768
	ds_write_b128 v119, v[74:77] offset:32768
	ds_write_b128 v120, v[78:81] offset:32768
	ds_write_b128 v121, v[82:85] offset:32768
	v_add_u32_e32 v118, 0x10000, v118
	v_add_u32_e32 v119, 0x10000, v119
	v_add_u32_e32 v120, 0x10000, v120
	v_add_u32_e32 v121, 0x10000, v121
	ds_write_b128 v118, v[86:89]
	ds_write_b128 v119, v[90:93]
	ds_write_b128 v120, v[94:97]
	ds_write_b128 v121, v[98:101]
	ds_write_b128 v118, v[102:105] offset:32768
	ds_write_b128 v119, v[106:109] offset:32768
	ds_write_b128 v120, v[110:113] offset:32768
	ds_write_b128 v121, v[114:117] offset:32768
	s_waitcnt lgkmcnt(0)
	s_barrier
	s_lshl_b32 s2, s50, 6
	v_or_b32_e32 v2, s2, v229
	v_ashrrev_i32_e32 v3, 31, v2
	v_bitop3_b32 v5, s2, v232, v229 bitop3:0xc8
	v_or_b32_e32 v4, 16, v2
	v_lshlrev_b64 v[174:175], 12, v[2:3]
	v_lshlrev_b64 v[6:7], 11, v[2:3]
	v_or_b32_e32 v8, 32, v2
	v_or_b32_e32 v2, 48, v2
	v_cmp_lt_u32_e32 vcc, 2, v5
	v_cmp_lt_u32_e64 s[2:3], 1, v5
	v_cmp_ne_u32_e64 s[4:5], 0, v5
	v_ashrrev_i32_e32 v5, 31, v4
	v_ashrrev_i32_e32 v9, 31, v8
	v_ashrrev_i32_e32 v3, 31, v2
	v_lshlrev_b64 v[188:189], 12, v[4:5]
	v_lshlrev_b64 v[196:197], 12, v[8:9]
	v_lshlrev_b64 v[4:5], 11, v[4:5]
	v_lshlrev_b64 v[204:205], 12, v[2:3]
	v_lshlrev_b64 v[8:9], 11, v[8:9]
	v_lshlrev_b64 v[2:3], 11, v[2:3]
	v_lshl_add_u64 v[176:177], v[174:175], 0, s[14:15]
	v_lshl_add_u64 v[178:179], v[174:175], 0, s[16:17]
	v_lshl_add_u64 v[180:181], v[174:175], 0, s[18:19]
	v_lshl_add_u64 v[182:183], v[174:175], 0, s[20:21]
	v_lshl_add_u64 v[184:185], v[174:175], 0, s[22:23]
	v_lshl_add_u64 v[186:187], v[174:175], 0, s[24:25]
	v_lshl_add_u64 v[190:191], v[174:175], 0, s[26:27]
	v_lshl_add_u64 v[192:193], v[174:175], 0, s[28:29]
	v_lshl_add_u64 v[194:195], v[174:175], 0, s[30:31]
	v_lshl_add_u64 v[198:199], v[174:175], 0, s[34:35]
	v_lshl_add_u64 v[200:201], v[174:175], 0, s[36:37]
	v_lshl_add_u64 v[202:203], v[174:175], 0, s[38:39]
	v_lshlrev_b64 v[206:207], 1, v[6:7]
	v_lshlrev_b64 v[208:209], 1, v[4:5]
	v_lshlrev_b64 v[210:211], 1, v[8:9]
	v_lshlrev_b64 v[212:213], 1, v[2:3]
	s_mov_b32 s51, 0
	v_mov_b32_e32 v66, v163
	v_mov_b32_e32 v67, v163
	v_mov_b32_e32 v68, v163
	v_mov_b32_e32 v69, v163
	v_mov_b32_e32 v62, v163
	v_mov_b32_e32 v63, v163
	v_mov_b32_e32 v64, v163
	v_mov_b32_e32 v65, v163
	v_mov_b32_e32 v2, v163
	v_mov_b32_e32 v3, v163
	v_mov_b32_e32 v4, v163
	v_mov_b32_e32 v5, v163
	v_mov_b32_e32 v6, v163
	v_mov_b32_e32 v7, v163
	v_mov_b32_e32 v8, v163
	v_mov_b32_e32 v9, v163
	s_branch .LBB0_301
